# attention: packed v_pk_mul_f32 O-rescale split into scalar v_mul pairs (bit-identical)
# baseline (speedup 1.0000x reference)
.LBB0_720:
	s_or_b64 exec, exec, s[10:11]
	s_and_b32 s13, 1, s12
	s_cselect_b32 s10, 0, 0x8c00
	s_add_i32 s10, s10, 16
	v_add3_u32 v114, s10, v158, v105
	ds_read_b128 v[118:121], v114
	ds_read_b128 v[122:125], v114 offset:64
	ds_read_b128 v[126:129], v114 offset:4352
	ds_read_b128 v[130:133], v114 offset:4416
	s_waitcnt lgkmcnt(3)
	v_mfma_f32_16x16x32_bf16 v[118:121], v[118:121], v[36:39], 0
	s_waitcnt lgkmcnt(1)
	v_mfma_f32_16x16x32_bf16 v[126:129], v[126:129], v[36:39], 0
	s_nop 0
	v_mfma_f32_16x16x32_bf16 v[118:121], v[122:125], v[40:43], v[118:121]
	ds_read_b128 v[122:125], v114 offset:8704
	s_waitcnt lgkmcnt(1)
	v_mfma_f32_16x16x32_bf16 v[126:129], v[130:133], v[40:43], v[126:129]
	ds_read_b128 v[130:133], v114 offset:8768
	ds_read_b128 v[138:141], v114 offset:13056
	ds_read_b128 v[160:163], v114 offset:13120
	s_waitcnt lgkmcnt(3)
	v_mfma_f32_16x16x32_bf16 v[122:125], v[122:125], v[36:39], 0
	s_waitcnt lgkmcnt(2)
	v_mfma_f32_16x16x32_bf16 v[130:133], v[130:133], v[40:43], v[122:125]
	s_nop 5
	v_max3_f32 v122, v118, s26, v119
	v_max3_f32 v122, v122, v120, v121
	v_max3_f32 v134, v122, v126, v127
	s_waitcnt lgkmcnt(1)
	v_mfma_f32_16x16x32_bf16 v[122:125], v[138:141], v[36:39], 0
	v_max3_f32 v134, v134, v128, v129
	v_max3_f32 v134, v134, v130, v131
	v_max3_f32 v134, v134, v132, v133
	s_waitcnt lgkmcnt(0)
	v_mfma_f32_16x16x32_bf16 v[138:141], v[160:163], v[40:43], v[122:125]
	s_nop 7
	v_max3_f32 v122, v134, v138, v139
	v_max3_f32 v122, v122, v140, v141
	v_mul_f32_e32 v122, 0x3e38aa3b, v122
	ds_bpermute_b32 v123, v149, v122
	s_waitcnt lgkmcnt(0)
	v_max_f32_e32 v123, v123, v123
	v_max_f32_e32 v134, v122, v123
	ds_bpermute_b32 v135, v148, v134
	ds_read_b128 v[122:125], v114 offset:128
	ds_read_b128 v[166:169], v114 offset:192
	ds_read_b128 v[170:173], v114 offset:4544
	s_waitcnt lgkmcnt(2)
	v_mfma_f32_16x16x32_bf16 v[122:125], v[122:125], v[48:51], 0
	v_max3_f32 v159, v117, v134, v135
	v_sub_f32_e32 v134, v117, v159
	v_fma_f32 v117, v118, s27, -v159
	v_fma_f32 v118, v119, s27, -v159
	v_fma_f32 v119, v120, s27, -v159
	v_fma_f32 v120, v121, s27, -v159
	v_exp_f32_e32 v162, v118
	v_exp_f32_e32 v163, v119
	v_exp_f32_e32 v164, v120
	ds_read_b128 v[118:121], v114 offset:4480
	s_waitcnt lgkmcnt(2)
	v_mfma_f32_16x16x32_bf16 v[174:177], v[166:169], v[52:55], v[122:125]
	v_exp_f32_e32 v161, v117
	v_fma_f32 v117, v126, s27, -v159
	v_exp_f32_e32 v165, v117
	ds_read_b128 v[122:125], v114 offset:8832
	s_waitcnt lgkmcnt(1)
	v_mfma_f32_16x16x32_bf16 v[118:121], v[118:121], v[48:51], 0
	v_fma_f32 v117, v127, s27, -v159
	v_exp_f32_e32 v166, v117
	v_fma_f32 v117, v128, s27, -v159
	v_fma_f32 v135, v129, s27, -v159
	ds_read_b128 v[126:129], v114 offset:8896
	v_mfma_f32_16x16x32_bf16 v[178:181], v[170:173], v[52:55], v[118:121]
	ds_read_b128 v[168:171], v114 offset:13184
	ds_read_b128 v[182:185], v114 offset:13248
	v_fma_f32 v114, v132, s27, -v159
	s_waitcnt lgkmcnt(3)
	v_mfma_f32_16x16x32_bf16 v[122:125], v[122:125], v[48:51], 0
	v_fma_f32 v118, v130, s27, -v159
	v_exp_f32_e32 v121, v118
	v_fma_f32 v118, v131, s27, -v159
	s_waitcnt lgkmcnt(2)
	v_mfma_f32_16x16x32_bf16 v[186:189], v[126:129], v[52:55], v[122:125]
	v_exp_f32_e32 v119, v135
	v_exp_f32_e32 v136, v134
	v_exp_f32_e32 v117, v117
	s_waitcnt lgkmcnt(1)
	v_mfma_f32_16x16x32_bf16 v[128:131], v[168:171], v[48:51], 0
	v_exp_f32_e32 v123, v118
	v_max3_f32 v118, v174, s26, v175
	v_max3_f32 v118, v118, v176, v177
	s_waitcnt lgkmcnt(0)
	v_mfma_f32_16x16x32_bf16 v[182:185], v[182:185], v[52:55], v[128:131]
	v_max3_f32 v118, v118, v178, v179
	v_max3_f32 v118, v118, v180, v181
	v_max3_f32 v118, v118, v186, v187
	v_max3_f32 v118, v118, v188, v189
	v_exp_f32_e32 v125, v114
	s_nop 2
	v_max3_f32 v118, v118, v182, v183
	v_max3_f32 v118, v118, v184, v185
	v_mul_f32_e32 v118, 0x3e38aa3b, v118
	ds_bpermute_b32 v120, v149, v118
	v_fma_f32 v114, v133, s27, -v159
	v_exp_f32_e32 v127, v114
	v_fma_f32 v114, v138, s27, -v159
	v_exp_f32_e32 v129, v114
	s_waitcnt lgkmcnt(0)
	v_max_f32_e32 v120, v120, v120
	v_max_f32_e32 v118, v118, v120
	ds_bpermute_b32 v120, v148, v118
	v_fma_f32 v114, v139, s27, -v159
	v_exp_f32_e32 v131, v114
	v_fma_f32 v114, v140, s27, -v159
	v_exp_f32_e32 v133, v114
	v_fma_f32 v114, v141, s27, -v159
	s_waitcnt lgkmcnt(0)
	v_max3_f32 v160, v116, v118, v120
	v_exp_f32_e32 v135, v114
	v_sub_f32_e32 v114, v116, v160
	v_fma_f32 v116, v174, s27, -v160
	v_exp_f32_e32 v167, v116
	v_fma_f32 v116, v175, s27, -v160
	v_exp_f32_e32 v168, v116
	v_fma_f32 v116, v176, s27, -v160
	v_exp_f32_e32 v169, v116
	v_fma_f32 v116, v177, s27, -v160
	v_exp_f32_e32 v138, v114
	v_lshlrev_b32_e32 v114, 1, v3
	v_exp_f32_e32 v170, v116
	v_fma_f32 v116, v178, s27, -v160
	v_add3_u32 v139, s10, v115, v114
	v_add3_u32 v178, s10, v152, v114
	v_add_u32_e32 v173, 0x4000, v139
	v_add_u32_e32 v190, 0x4000, v178
	v_fma_f32 v128, v182, s27, -v160
	v_fma_f32 v130, v183, s27, -v160
	v_fma_f32 v132, v184, s27, -v160
	v_fma_f32 v134, v185, s27, -v160
	ds_read2_b64 v[174:177], v173 offset0:128 offset1:132
	ds_read2_b64 v[182:185], v190 offset0:128 offset1:132
	v_exp_f32_e32 v171, v116
	v_fma_f32 v116, v179, s27, -v160
	v_exp_f32_e32 v172, v116
	v_fma_f32 v116, v180, s27, -v160
	v_fma_f32 v118, v181, s27, -v160
	v_exp_f32_e32 v116, v116
	v_exp_f32_e32 v118, v118
	v_mul_f32_e32 v98, v136, v98
	v_mul_f32_e32 v99, v136, v99
	v_mul_f32_e32 v96, v136, v96
	v_mul_f32_e32 v97, v136, v97
	v_mul_f32_e32 v94, v136, v94
	v_mul_f32_e32 v95, v136, v95
	v_mul_f32_e32 v92, v136, v92
	v_mul_f32_e32 v93, v136, v93
	v_cvt_pk_bf16_f32 v143, v117, v119
	v_cvt_pk_bf16_f32 v142, v165, v166
	v_cvt_pk_bf16_f32 v141, v163, v164
	v_cvt_pk_bf16_f32 v140, v161, v162
	v_mul_f32_e32 v82, v138, v82
	v_mul_f32_e32 v83, v138, v83
	v_mul_f32_e32 v80, v138, v80
	v_mul_f32_e32 v81, v138, v81
	v_cvt_pk_bf16_f32 v181, v116, v118
	v_cvt_pk_bf16_f32 v180, v171, v172
	v_cvt_pk_bf16_f32 v179, v169, v170
	v_cvt_pk_bf16_f32 v178, v167, v168
	v_mul_f32_e32 v70, v138, v70
	v_mul_f32_e32 v71, v138, v71
	v_mul_f32_e32 v68, v138, v68
	v_mul_f32_e32 v69, v138, v69
	s_waitcnt lgkmcnt(1)
	v_mfma_f32_16x16x32_bf16 v[96:99], v[174:177], v[140:143], v[96:99]
	v_mul_f32_e64 v78, v78, v136
	v_mul_f32_e64 v79, v79, v136
	v_mul_f32_e32 v76, v136, v76
	v_mul_f32_e32 v77, v136, v77
	v_mul_f32_e32 v74, v136, v74
	v_mul_f32_e32 v75, v136, v75
	v_mfma_f32_16x16x32_bf16 v[80:83], v[174:177], v[178:181], v[80:83]
	v_add3_u32 v174, s10, v153, v114
	v_add_u32_e32 v191, 0x4000, v174
	ds_read2_b64 v[174:177], v191 offset0:128 offset1:132
	s_waitcnt lgkmcnt(1)
	v_mfma_f32_16x16x32_bf16 v[92:95], v[182:185], v[140:143], v[92:95]
	v_mul_f32_e64 v58, v58, v138
	v_mul_f32_e64 v59, v59, v138
	v_mul_f32_e32 v56, v138, v56
	v_mul_f32_e32 v57, v138, v57
	v_mul_f32_e32 v72, v136, v72
	v_mul_f32_e32 v73, v136, v73
	v_mfma_f32_16x16x32_bf16 v[68:71], v[182:185], v[178:181], v[68:71]
	v_add3_u32 v182, s10, v154, v114
	v_add_u32_e32 v192, 0x4000, v182
	ds_read2_b64 v[182:185], v192 offset0:128 offset1:132
	v_add_u32_e32 v193, 0x6800, v139
	v_mul_f32_e32 v26, v138, v26
	v_mul_f32_e32 v27, v138, v27
	v_mul_f32_e32 v24, v138, v24
	v_mul_f32_e32 v25, v138, v25
	v_add_u32_e32 v194, 0x7000, v139
	s_waitcnt lgkmcnt(1)
	v_mfma_f32_16x16x32_bf16 v[76:79], v[174:177], v[140:143], v[76:79]
	v_mul_f32_e64 v62, v62, v136
	v_mul_f32_e64 v63, v63, v136
	v_mul_f32_e32 v60, v136, v60
	v_mul_f32_e32 v61, v136, v61
	v_mul_f32_e32 v30, v136, v30
	v_mul_f32_e32 v31, v136, v31
	v_mfma_f32_16x16x32_bf16 v[56:59], v[174:177], v[178:181], v[56:59]
	ds_read2_b64 v[174:177], v193 offset1:4
	v_mul_f32_e32 v66, v138, v66
	v_mul_f32_e32 v67, v138, v67
	v_mul_f32_e32 v64, v138, v64
	v_mul_f32_e32 v65, v138, v65
	s_waitcnt lgkmcnt(1)
	v_mfma_f32_16x16x32_bf16 v[72:75], v[182:185], v[140:143], v[72:75]
	v_mul_f32_e64 v28, v28, v136
	v_mul_f32_e64 v29, v29, v136
	v_add_u32_e32 v195, 0x7800, v139
	v_mul_f32_e32 v46, v138, v46
	v_mul_f32_e32 v47, v138, v47
	v_mfma_f32_16x16x32_bf16 v[24:27], v[182:185], v[178:181], v[24:27]
	ds_read2_b64 v[182:185], v194 offset0:32 offset1:36
	v_mul_f32_e32 v44, v138, v44
	v_mul_f32_e32 v45, v138, v45
	v_add_u32_e32 v139, 0x8000, v139
	s_waitcnt lgkmcnt(1)
	v_mfma_f32_16x16x32_bf16 v[60:63], v[174:177], v[140:143], v[60:63]
	v_mul_f32_e64 v34, v34, v138
	v_mul_f32_e64 v35, v35, v138
	v_mul_f32_e32 v32, v138, v32
	v_mul_f32_e32 v33, v138, v33
	v_mul_f32_e32 v90, v138, v90
	v_mul_f32_e32 v91, v138, v91
	v_mfma_f32_16x16x32_bf16 v[64:67], v[174:177], v[178:181], v[64:67]
	ds_read2_b64 v[174:177], v195 offset0:64 offset1:68
	v_mul_f32_e32 v88, v138, v88
	v_mul_f32_e32 v89, v138, v89
	v_fma_f32 v120, v186, s27, -v160
	s_waitcnt lgkmcnt(1)
	v_mfma_f32_16x16x32_bf16 v[28:31], v[182:185], v[140:143], v[28:31]
	v_fma_f32 v122, v187, s27, -v160
	v_fma_f32 v124, v188, s27, -v160
	v_fma_f32 v126, v189, s27, -v160
	v_mfma_f32_16x16x32_bf16 v[44:47], v[182:185], v[178:181], v[44:47]
	ds_read2_b64 v[182:185], v139 offset0:96 offset1:100
	v_exp_f32_e32 v120, v120
	v_exp_f32_e32 v122, v122
	s_waitcnt lgkmcnt(1)
	v_mfma_f32_16x16x32_bf16 v[32:35], v[174:177], v[178:181], v[32:35]
	v_exp_f32_e32 v124, v124
	v_exp_f32_e32 v126, v126
	v_exp_f32_e32 v128, v128
	s_waitcnt lgkmcnt(0)
	v_mfma_f32_16x16x32_bf16 v[88:91], v[182:185], v[178:181], v[88:91]
	ds_read2_b64 v[178:181], v190 offset0:136 offset1:140
	v_exp_f32_e32 v130, v130
	v_exp_f32_e32 v132, v132
	v_exp_f32_e32 v134, v134
	v_mul_f32_e32 v22, v136, v22
	v_mul_f32_e32 v23, v136, v23
	v_mul_f32_e32 v20, v136, v20
	v_mul_f32_e32 v21, v136, v21
	v_mul_f32_e32 v86, v136, v86
	v_mul_f32_e32 v87, v136, v87
	v_mul_f32_e32 v84, v136, v84
	v_mul_f32_e32 v85, v136, v85
	v_mfma_f32_16x16x32_bf16 v[20:23], v[174:177], v[140:143], v[20:23]
	v_cvt_pk_bf16_f32 v177, v133, v135
	v_cvt_pk_bf16_f32 v176, v129, v131
	v_cvt_pk_bf16_f32 v175, v125, v127
	v_mfma_f32_16x16x32_bf16 v[84:87], v[182:185], v[140:143], v[84:87]
	v_cvt_pk_bf16_f32 v174, v121, v123
	v_cvt_pk_bf16_f32 v143, v132, v134
	v_cvt_pk_bf16_f32 v142, v128, v130
	v_cvt_pk_bf16_f32 v141, v124, v126
	v_cvt_pk_bf16_f32 v140, v120, v122
	s_waitcnt lgkmcnt(0)
	v_mfma_f32_16x16x32_bf16 v[92:95], v[178:181], v[174:177], v[92:95]
	ds_read2_b64 v[186:189], v173 offset0:136 offset1:140
	v_mfma_f32_16x16x32_bf16 v[68:71], v[178:181], v[140:143], v[68:71]
	ds_read2_b64 v[178:181], v191 offset0:136 offset1:140
	s_waitcnt lgkmcnt(0)
	v_mfma_f32_16x16x32_bf16 v[76:79], v[178:181], v[174:177], v[76:79]
	v_mfma_f32_16x16x32_bf16 v[56:59], v[178:181], v[140:143], v[56:59]
	ds_read2_b64 v[178:181], v192 offset0:136 offset1:140
	s_waitcnt lgkmcnt(0)
	v_mfma_f32_16x16x32_bf16 v[72:75], v[178:181], v[174:177], v[72:75]
	v_mfma_f32_16x16x32_bf16 v[24:27], v[178:181], v[140:143], v[24:27]
	ds_read2_b64 v[178:181], v193 offset0:8 offset1:12
	s_waitcnt lgkmcnt(0)
	v_mfma_f32_16x16x32_bf16 v[60:63], v[178:181], v[174:177], v[60:63]
	v_mfma_f32_16x16x32_bf16 v[64:67], v[178:181], v[140:143], v[64:67]
	ds_read2_b64 v[178:181], v194 offset0:40 offset1:44
	s_waitcnt lgkmcnt(0)
	v_mfma_f32_16x16x32_bf16 v[28:31], v[178:181], v[174:177], v[28:31]
	v_mfma_f32_16x16x32_bf16 v[44:47], v[178:181], v[140:143], v[44:47]
	ds_read2_b64 v[178:181], v195 offset0:72 offset1:76
	s_waitcnt lgkmcnt(0)
	v_mfma_f32_16x16x32_bf16 v[20:23], v[178:181], v[174:177], v[20:23]
	v_mfma_f32_16x16x32_bf16 v[32:35], v[178:181], v[140:143], v[32:35]
	ds_read2_b64 v[178:181], v139 offset0:104 offset1:108
	v_mfma_f32_16x16x32_bf16 v[96:99], v[186:189], v[174:177], v[96:99]
	v_mfma_f32_16x16x32_bf16 v[80:83], v[186:189], v[140:143], v[80:83]
	s_waitcnt lgkmcnt(0)
	v_mfma_f32_16x16x32_bf16 v[84:87], v[178:181], v[174:177], v[84:87]
	v_mfma_f32_16x16x32_bf16 v[88:91], v[178:181], v[140:143], v[88:91]
	s_and_saveexec_b64 s[10:11], s[6:7]
	s_cbranch_execz .LBB0_717
	s_cmp_eq_u32 s13, 1
	s_cselect_b32 s6, 0x8c00, 0
	s_add_i32 s6, s6, 16
	v_add3_u32 v139, s6, v155, v102
	s_waitcnt vmcnt(0)
	ds_write_b128 v139, v[4:7]
	ds_write_b128 v139, v[8:11] offset:8704
	v_add3_u32 v139, s6, v156, v104
	ds_write_b128 v139, v[12:15] offset:17408
	ds_write_b128 v139, v[16:19] offset:26624
	s_branch .LBB0_717
